# v61 + GEMM K-loops: static s_setprio 1 for the wave half that enters first (waves 0-3), no per-segment toggling
# speedup vs baseline: 1.0031x; 1.0031x over previous
; template <class Epi, class Sched, bool ALIGN_EPI = false, bool SP2 = false>
; __device__ __forceinline__ void gemm_phase(PG8_LAS unsigned char* lds, const Gemm g, const Sched& S, const Epi& E) {
;     ...
;         const bool has_next = S.next(ui + 1, nxt);
;         const char* nA = has_next ? (const char*)g.A + (size_t)nxt.pm * tstep : cA; const char* nB = has_next ? (const char*)g.Bt + (size_t)nxt.pn * tstep : cB;
;         for (int t = 0; t < nt; t += 2) {
;             const bool last = (t == nt - 2);
;             const char* a1 = cA + (size_t)(t + 1) * kstep;
;             const char* a2 = last ? nA : cA + (size_t)(t + 2) * kstep; const char* b2 = last ? nB : cB + (size_t)(t + 2) * kstep;
;             const char* a3 = a2 + kstep; const char* b3 = b2 + kstep;
.LBB0_184:
	s_ashr_i32 s23, s22, 31
	s_lshl_b64 s[24:25], s[22:23], 19
	s_add_u32 s24, s2, s24
	s_addc_u32 s25, s36, s25
	s_and_b64 s[26:27], s[8:9], exec
	s_cselect_b32 s23, s25, s29
	s_cselect_b32 s33, s24, s28
	s_ashr_i32 s21, s20, 31
	s_lshl_b64 s[26:27], s[20:21], 19
	s_add_u32 s26, s37, s26
	s_addc_u32 s27, s38, s27
	s_and_b64 s[34:35], s[8:9], exec
	s_cselect_b32 s21, s27, s31
	s_cselect_b32 s51, s26, s30
	s_add_u32 s28, s28, 0x40080
	s_addc_u32 s29, s29, 0
	s_add_u32 s52, s30, 0x100
	s_addc_u32 s53, s31, 0
	s_mov_b32 s54, -2
	s_cmp_eq_u64 s[16:17], 0
	s_cbranch_scc1 .Lmy_prio_185
	s_setprio 1

; template <class Epi, class Sched, bool ALIGN_EPI = false, bool SP2 = false>
; __device__ __forceinline__ void gemm_phase(PG8_LAS unsigned char* lds, const Gemm g, const Sched& S, const Epi& E) {
;     ...
;         const bool has_next = S.next(ui + 1, nxt);
;         const char* nA = has_next ? (const char*)g.A + (size_t)nxt.pm * tstep : cA; const char* nB = has_next ? (const char*)g.Bt + (size_t)nxt.pn * tstep : cB;
;         for (int t = 0; t < nt; t += 2) {
;             const bool last = (t == nt - 2);
;             const char* a1 = cA + (size_t)(t + 1) * kstep;
;             const char* a2 = last ? nA : cA + (size_t)(t + 2) * kstep; const char* b2 = last ? nB : cB + (size_t)(t + 2) * kstep;
;             const char* a3 = a2 + kstep; const char* b3 = b2 + kstep;
.LBB0_632:
	s_ashr_i32 s29, s28, 31
	s_lshl_b64 s[30:31], s[28:29], 19
	s_add_u32 s30, s38, s30
	s_addc_u32 s31, s39, s31
	s_and_b64 s[34:35], s[8:9], exec
	s_cselect_b32 s5, s31, s11
	s_cselect_b32 s25, s30, s10
	s_ashr_i32 s27, s26, 31
	s_lshl_b64 s[34:35], s[26:27], 19
	s_add_u32 s34, s40, s34
	s_addc_u32 s35, s41, s35
	s_and_b64 s[36:37], s[8:9], exec
	s_cselect_b32 s27, s35, s13
	s_cselect_b32 s29, s34, s12
	s_add_u32 s10, s10, 0x40080
	s_addc_u32 s11, s11, 0
	s_add_u32 s33, s12, 0x100
	s_addc_u32 s54, s13, 0
	s_mov_b32 s55, -2
	s_waitcnt lgkmcnt(0)
	s_cmp_eq_u64 s[20:21], 0
	s_cbranch_scc1 .Lmy_prio_633
	s_setprio 1

; template <class Epi, class Sched, bool ALIGN_EPI = false, bool SP2 = false>
; __device__ __forceinline__ void gemm_phase(PG8_LAS unsigned char* lds, const Gemm g, const Sched& S, const Epi& E) {
;     ...
;         const bool has_next = S.next(ui + 1, nxt);
;         const char* nA = has_next ? (const char*)g.A + (size_t)nxt.pm * tstep : cA; const char* nB = has_next ? (const char*)g.Bt + (size_t)nxt.pn * tstep : cB;
;         for (int t = 0; t < nt; t += 2) {
;             const bool last = (t == nt - 2);
;             const char* a1 = cA + (size_t)(t + 1) * kstep;
;             const char* a2 = last ? nA : cA + (size_t)(t + 2) * kstep; const char* b2 = last ? nB : cB + (size_t)(t + 2) * kstep;
;             const char* a3 = a2 + kstep; const char* b3 = b2 + kstep;
.LBB0_811:
	s_ashr_i32 s19, s18, 31
	s_lshl_b64 s[20:21], s[18:19], 19
	s_add_u32 s20, s2, s20
	s_addc_u32 s21, s30, s21
	s_and_b64 s[22:23], s[6:7], exec
	s_cselect_b32 s19, s21, s25
	s_cselect_b32 s33, s20, s24
	s_ashr_i32 s17, s16, 31
	s_lshl_b64 s[22:23], s[16:17], 19
	s_add_u32 s22, s31, s22
	s_addc_u32 s23, s34, s23
	s_and_b64 s[28:29], s[6:7], exec
	s_cselect_b32 s17, s23, s27
	s_cselect_b32 s45, s22, s26
	s_add_u32 s24, s24, 0x40080
	s_addc_u32 s25, s25, 0
	s_add_u32 s46, s26, 0x100
	s_addc_u32 s47, s27, 0
	s_mov_b32 s48, -2
	s_cmp_eq_u64 s[14:15], 0
	s_cbranch_scc1 .Lmy_prio_812
	s_setprio 1

; template <class Epi, class Sched, bool ALIGN_EPI = false, bool SP2 = false>
; __device__ __forceinline__ void gemm_phase(PG8_LAS unsigned char* lds, const Gemm g, const Sched& S, const Epi& E) {
;     ...
;         const bool has_next = S.next(ui + 1, nxt);
;         const char* nA = has_next ? (const char*)g.A + (size_t)nxt.pm * tstep : cA; const char* nB = has_next ? (const char*)g.Bt + (size_t)nxt.pn * tstep : cB;
;         for (int t = 0; t < nt; t += 2) {
;             const bool last = (t == nt - 2);
;             const char* a1 = cA + (size_t)(t + 1) * kstep;
;             const char* a2 = last ? nA : cA + (size_t)(t + 2) * kstep; const char* b2 = last ? nB : cB + (size_t)(t + 2) * kstep;
;             const char* a3 = a2 + kstep; const char* b3 = b2 + kstep;
.LBB0_1074:
	s_ashr_i32 s29, s28, 31
	s_lshl_b64 s[30:31], s[28:29], 19
	s_add_u32 s30, s2, s30
	s_addc_u32 s31, s39, s31
	s_and_b64 s[34:35], s[6:7], exec
	s_cselect_b32 s5, s31, s9
	s_cselect_b32 s25, s30, s8
	s_ashr_i32 s27, s26, 31
	s_lshl_b64 s[34:35], s[26:27], 19
	s_add_u32 s34, s40, s34
	s_addc_u32 s35, s41, s35
	s_and_b64 s[36:37], s[6:7], exec
	s_cselect_b32 s27, s35, s11
	s_cselect_b32 s29, s34, s10
	s_add_u32 s8, s8, 0x40080
	s_addc_u32 s9, s9, 0
	s_add_u32 s33, s10, 0x100
	s_addc_u32 s54, s11, 0
	s_mov_b32 s55, -2
	s_waitcnt lgkmcnt(0)
	s_cmp_eq_u64 s[20:21], 0
	s_cbranch_scc1 .Lmy_prio_1075
	s_setprio 1

; template <class Epi, class Sched, bool ALIGN_EPI = false, bool SP2 = false>
; __device__ __forceinline__ void gemm_phase(PG8_LAS unsigned char* lds, const Gemm g, const Sched& S, const Epi& E) {
;     ...
;         const bool has_next = S.next(ui + 1, nxt);
;         const char* nA = has_next ? (const char*)g.A + (size_t)nxt.pm * tstep : cA; const char* nB = has_next ? (const char*)g.Bt + (size_t)nxt.pn * tstep : cB;
;         for (int t = 0; t < nt; t += 2) {
;             const bool last = (t == nt - 2);
;             const char* a1 = cA + (size_t)(t + 1) * kstep;
;             const char* a2 = last ? nA : cA + (size_t)(t + 2) * kstep; const char* b2 = last ? nB : cB + (size_t)(t + 2) * kstep;
;             const char* a3 = a2 + kstep; const char* b3 = b2 + kstep;
.LBB0_1246:
	s_ashr_i32 s37, s36, 31
	s_lshl_b64 s[8:9], s[36:37], 19
	s_add_u32 s38, s2, s8
	s_addc_u32 s39, s49, s9
	s_and_b64 s[8:9], s[6:7], exec
	s_cselect_b32 s37, s39, s47
	s_cselect_b32 s43, s38, s46
	s_ashr_i32 s35, s34, 31
	s_lshl_b64 s[8:9], s[34:35], 19
	s_add_u32 s40, s50, s8
	s_addc_u32 s41, s51, s9
	s_and_b64 s[8:9], s[6:7], exec
	s_cselect_b32 s35, s41, s45
	s_cselect_b32 s65, s40, s44
	s_add_u32 s8, s46, 0x40080
	s_addc_u32 s9, s47, 0
	s_add_u32 s66, s44, 0x100
	s_addc_u32 s67, s45, 0
	s_mov_b32 s68, -2
	s_cmp_eq_u64 s[24:25], 0
	s_cbranch_scc1 .Lmy_prio_1247
	s_setprio 1

; template <class Epi, class Sched, bool ALIGN_EPI = false, bool SP2 = false>
; __device__ __forceinline__ void gemm_phase(PG8_LAS unsigned char* lds, const Gemm g, const Sched& S, const Epi& E) {
;     ...
;         for (int t = 0; t < nt; t += 2) {
;             const bool last = (t == nt - 2);
;             const char* a1 = cA + (size_t)(t + 1) * kstep;
;             const char* a2 = last ? nA : cA + (size_t)(t + 2) * kstep; const char* b2 = last ? nB : cB + (size_t)(t + 2) * kstep;
;             const char* a3 = a2 + kstep; const char* b3 = b2 + kstep;
.LBB0_1359:
	s_add_u32 s33, s24, 0x100
	s_addc_u32 s49, s25, 0
	s_mov_b32 s50, -2
	s_waitcnt lgkmcnt(0)
	s_cmp_eq_u64 s[14:15], 0
	s_cbranch_scc1 .Lmy_prio_1360
	s_setprio 1
